# v24 + mod phase: all 8 c loads issued before the silu math; weight-prep shift@W loops: all 32 shift-vector loads issued up front (one latency instead of four)
# speedup vs baseline: 1.0365x; 1.0078x over previous
; __device__ __forceinline__ void transpose_item(const float* W, int K, int N, bf16_t* WT, int k0, int src_n0, int dst_n0, LAS float* scr, int lane, const float* st, float* sw, const float* gt, size_t cstride) {
;     ...
;     if (st) { const int n = lane & 31, hf = lane >> 5; f32x4 a4 = {0.f, 0.f, 0.f, 0.f};
; #pragma unroll 8
;         for (int i = 0; i < 32; ++i) { const int kk = hf * 32 + i; a4 += *(const f32x4*)(st + (size_t)(k0 + kk) * NB) * scr[kk * 33 + n]; }
.LBB0_34:
	global_load_dwordx4 v[6:9], v[4:5], off offset:-64
	global_load_dwordx4 v[10:13], v[4:5], off offset:-48
	global_load_dwordx4 v[14:17], v[4:5], off offset:-32
	global_load_dwordx4 v[18:21], v[4:5], off offset:-16
	global_load_dwordx4 v[22:25], v[4:5], off
	global_load_dwordx4 v[26:29], v[4:5], off offset:16
	global_load_dwordx4 v[30:33], v[4:5], off offset:32
	global_load_dwordx4 v[42:45], v[4:5], off offset:48
	global_load_dwordx4 v[122:125], v[4:5], off offset:64
	global_load_dwordx4 v[126:129], v[4:5], off offset:80
	global_load_dwordx4 v[130:133], v[4:5], off offset:96
	global_load_dwordx4 v[134:137], v[4:5], off offset:112
	global_load_dwordx4 v[138:141], v[4:5], off offset:128
	global_load_dwordx4 v[142:145], v[4:5], off offset:144
	global_load_dwordx4 v[146:149], v[4:5], off offset:160
	global_load_dwordx4 v[150:153], v[4:5], off offset:176
	global_load_dwordx4 v[186:189], v[4:5], off offset:192
	global_load_dwordx4 v[190:193], v[4:5], off offset:208
	global_load_dwordx4 v[194:197], v[4:5], off offset:224
	global_load_dwordx4 v[198:201], v[4:5], off offset:240
	global_load_dwordx4 v[202:205], v[4:5], off offset:256
	global_load_dwordx4 v[206:209], v[4:5], off offset:272
	global_load_dwordx4 v[210:213], v[4:5], off offset:288
	global_load_dwordx4 v[214:217], v[4:5], off offset:304
	global_load_dwordx4 v[154:157], v[4:5], off offset:320
	global_load_dwordx4 v[158:161], v[4:5], off offset:336
	global_load_dwordx4 v[162:165], v[4:5], off offset:352
	global_load_dwordx4 v[230:233], v[4:5], off offset:368
	global_load_dwordx4 v[234:237], v[4:5], off offset:384
	global_load_dwordx4 v[238:241], v[4:5], off offset:400
	global_load_dwordx4 v[242:245], v[4:5], off offset:416
	global_load_dwordx4 v[218:221], v[4:5], off offset:432
	v_add_u32_e32 v41, s5, v83
	ds_read2_b32 v[34:35], v41 offset1:33
	ds_read2_b32 v[46:47], v41 offset0:66 offset1:99
	ds_read2_b32 v[48:49], v41 offset0:132 offset1:165
	ds_read2_b32 v[50:51], v41 offset0:198 offset1:231
	s_addk_i32 s5, 0x420
	s_waitcnt lgkmcnt(3)
	v_mov_b32_e32 v52, v35
	s_waitcnt lgkmcnt(2)
	v_mov_b32_e32 v54, v47
	s_waitcnt lgkmcnt(1)
	v_mov_b32_e32 v56, v49
	s_waitcnt lgkmcnt(0)
	v_mov_b32_e32 v58, v51
	s_waitcnt vmcnt(31)
	v_pk_fma_f32 v[2:3], v[8:9], v[34:35], v[2:3] op_sel_hi:[1,0,1]
	v_pk_fma_f32 v[0:1], v[6:7], v[34:35], v[0:1] op_sel_hi:[1,0,1]
	s_waitcnt vmcnt(30)
	v_pk_fma_f32 v[2:3], v[12:13], v[52:53], v[2:3] op_sel_hi:[1,0,1]
	v_pk_fma_f32 v[0:1], v[10:11], v[52:53], v[0:1] op_sel_hi:[1,0,1]
	s_waitcnt vmcnt(29)
	v_pk_fma_f32 v[2:3], v[16:17], v[46:47], v[2:3] op_sel_hi:[1,0,1]
	v_pk_fma_f32 v[0:1], v[14:15], v[46:47], v[0:1] op_sel_hi:[1,0,1]
	s_waitcnt vmcnt(28)
	v_pk_fma_f32 v[2:3], v[20:21], v[54:55], v[2:3] op_sel_hi:[1,0,1]
	v_pk_fma_f32 v[0:1], v[18:19], v[54:55], v[0:1] op_sel_hi:[1,0,1]
	s_waitcnt vmcnt(27)
	v_pk_fma_f32 v[2:3], v[24:25], v[48:49], v[2:3] op_sel_hi:[1,0,1]
	v_pk_fma_f32 v[0:1], v[22:23], v[48:49], v[0:1] op_sel_hi:[1,0,1]
	s_waitcnt vmcnt(26)
	v_pk_fma_f32 v[2:3], v[28:29], v[56:57], v[2:3] op_sel_hi:[1,0,1]
	v_pk_fma_f32 v[0:1], v[26:27], v[56:57], v[0:1] op_sel_hi:[1,0,1]
	s_waitcnt vmcnt(25)
	v_pk_fma_f32 v[2:3], v[32:33], v[50:51], v[2:3] op_sel_hi:[1,0,1]
	v_pk_fma_f32 v[0:1], v[30:31], v[50:51], v[0:1] op_sel_hi:[1,0,1]
	s_waitcnt vmcnt(24)
	v_pk_fma_f32 v[2:3], v[44:45], v[58:59], v[2:3] op_sel_hi:[1,0,1]
	v_pk_fma_f32 v[0:1], v[42:43], v[58:59], v[0:1] op_sel_hi:[1,0,1]
	v_add_u32_e32 v41, s5, v83
	ds_read2_b32 v[34:35], v41 offset1:33
	ds_read2_b32 v[46:47], v41 offset0:66 offset1:99
	ds_read2_b32 v[48:49], v41 offset0:132 offset1:165
	ds_read2_b32 v[50:51], v41 offset0:198 offset1:231
	s_addk_i32 s5, 0x420
	s_waitcnt lgkmcnt(3)
	v_mov_b32_e32 v52, v35
	s_waitcnt lgkmcnt(2)
	v_mov_b32_e32 v54, v47
	s_waitcnt lgkmcnt(1)
	v_mov_b32_e32 v56, v49
	s_waitcnt lgkmcnt(0)
	v_mov_b32_e32 v58, v51
	s_waitcnt vmcnt(23)
	v_pk_fma_f32 v[2:3], v[124:125], v[34:35], v[2:3] op_sel_hi:[1,0,1]
	v_pk_fma_f32 v[0:1], v[122:123], v[34:35], v[0:1] op_sel_hi:[1,0,1]
	s_waitcnt vmcnt(22)
	v_pk_fma_f32 v[2:3], v[128:129], v[52:53], v[2:3] op_sel_hi:[1,0,1]
	v_pk_fma_f32 v[0:1], v[126:127], v[52:53], v[0:1] op_sel_hi:[1,0,1]
	s_waitcnt vmcnt(21)
	v_pk_fma_f32 v[2:3], v[132:133], v[46:47], v[2:3] op_sel_hi:[1,0,1]
	v_pk_fma_f32 v[0:1], v[130:131], v[46:47], v[0:1] op_sel_hi:[1,0,1]
	s_waitcnt vmcnt(20)
	v_pk_fma_f32 v[2:3], v[136:137], v[54:55], v[2:3] op_sel_hi:[1,0,1]
	v_pk_fma_f32 v[0:1], v[134:135], v[54:55], v[0:1] op_sel_hi:[1,0,1]
	s_waitcnt vmcnt(19)
	v_pk_fma_f32 v[2:3], v[140:141], v[48:49], v[2:3] op_sel_hi:[1,0,1]
	v_pk_fma_f32 v[0:1], v[138:139], v[48:49], v[0:1] op_sel_hi:[1,0,1]
	s_waitcnt vmcnt(18)
	v_pk_fma_f32 v[2:3], v[144:145], v[56:57], v[2:3] op_sel_hi:[1,0,1]
	v_pk_fma_f32 v[0:1], v[142:143], v[56:57], v[0:1] op_sel_hi:[1,0,1]
	s_waitcnt vmcnt(17)
; __device__ __forceinline__ void transpose_item(const float* W, int K, int N, bf16_t* WT, int k0, int src_n0, int dst_n0, LAS float* scr, int lane, const float* st, float* sw, const float* gt, size_t cstride) {
;     ...
;     if (st) { const int n = lane & 31, hf = lane >> 5; f32x4 a4 = {0.f, 0.f, 0.f, 0.f};
; #pragma unroll 8
;         for (int i = 0; i < 32; ++i) { const int kk = hf * 32 + i; a4 += *(const f32x4*)(st + (size_t)(k0 + kk) * NB) * scr[kk * 33 + n]; }
; #pragma unroll
;         for (int b = 0; b < 4; ++b) a4[b] += __shfl_xor(a4[b], 32);
;         if (hf == 0) {
; #pragma unroll
;             for (int b = 0; b < 4; ++b) __hip_atomic_fetch_add(sw + (size_t)b * NSW + dst_n0 + n, a4[b], __ATOMIC_RELAXED, __HIP_MEMORY_SCOPE_AGENT); } }
	v_pk_fma_f32 v[2:3], v[148:149], v[50:51], v[2:3] op_sel_hi:[1,0,1]
	v_pk_fma_f32 v[0:1], v[146:147], v[50:51], v[0:1] op_sel_hi:[1,0,1]
	s_waitcnt vmcnt(16)
	v_pk_fma_f32 v[2:3], v[152:153], v[58:59], v[2:3] op_sel_hi:[1,0,1]
	v_pk_fma_f32 v[0:1], v[150:151], v[58:59], v[0:1] op_sel_hi:[1,0,1]
	v_add_u32_e32 v41, s5, v83
	ds_read2_b32 v[34:35], v41 offset1:33
	ds_read2_b32 v[46:47], v41 offset0:66 offset1:99
	ds_read2_b32 v[48:49], v41 offset0:132 offset1:165
	ds_read2_b32 v[50:51], v41 offset0:198 offset1:231
	s_addk_i32 s5, 0x420
	s_waitcnt lgkmcnt(3)
	v_mov_b32_e32 v52, v35
	s_waitcnt lgkmcnt(2)
	v_mov_b32_e32 v54, v47
	s_waitcnt lgkmcnt(1)
	v_mov_b32_e32 v56, v49
	s_waitcnt lgkmcnt(0)
	v_mov_b32_e32 v58, v51
	s_waitcnt vmcnt(15)
	v_pk_fma_f32 v[2:3], v[188:189], v[34:35], v[2:3] op_sel_hi:[1,0,1]
	v_pk_fma_f32 v[0:1], v[186:187], v[34:35], v[0:1] op_sel_hi:[1,0,1]
	s_waitcnt vmcnt(14)
	v_pk_fma_f32 v[2:3], v[192:193], v[52:53], v[2:3] op_sel_hi:[1,0,1]
	v_pk_fma_f32 v[0:1], v[190:191], v[52:53], v[0:1] op_sel_hi:[1,0,1]
	s_waitcnt vmcnt(13)
	v_pk_fma_f32 v[2:3], v[196:197], v[46:47], v[2:3] op_sel_hi:[1,0,1]
	v_pk_fma_f32 v[0:1], v[194:195], v[46:47], v[0:1] op_sel_hi:[1,0,1]
	s_waitcnt vmcnt(12)
	v_pk_fma_f32 v[2:3], v[200:201], v[54:55], v[2:3] op_sel_hi:[1,0,1]
	v_pk_fma_f32 v[0:1], v[198:199], v[54:55], v[0:1] op_sel_hi:[1,0,1]
	s_waitcnt vmcnt(11)
	v_pk_fma_f32 v[2:3], v[204:205], v[48:49], v[2:3] op_sel_hi:[1,0,1]
	v_pk_fma_f32 v[0:1], v[202:203], v[48:49], v[0:1] op_sel_hi:[1,0,1]
	s_waitcnt vmcnt(10)
	v_pk_fma_f32 v[2:3], v[208:209], v[56:57], v[2:3] op_sel_hi:[1,0,1]
	v_pk_fma_f32 v[0:1], v[206:207], v[56:57], v[0:1] op_sel_hi:[1,0,1]
	s_waitcnt vmcnt(9)
	v_pk_fma_f32 v[2:3], v[212:213], v[50:51], v[2:3] op_sel_hi:[1,0,1]
	v_pk_fma_f32 v[0:1], v[210:211], v[50:51], v[0:1] op_sel_hi:[1,0,1]
	s_waitcnt vmcnt(8)
	v_pk_fma_f32 v[2:3], v[216:217], v[58:59], v[2:3] op_sel_hi:[1,0,1]
	v_pk_fma_f32 v[0:1], v[214:215], v[58:59], v[0:1] op_sel_hi:[1,0,1]
	v_add_u32_e32 v41, s5, v83
	ds_read2_b32 v[34:35], v41 offset1:33
	ds_read2_b32 v[46:47], v41 offset0:66 offset1:99
	ds_read2_b32 v[48:49], v41 offset0:132 offset1:165
	ds_read2_b32 v[50:51], v41 offset0:198 offset1:231
	s_addk_i32 s5, 0x420
	s_waitcnt lgkmcnt(3)
	v_mov_b32_e32 v52, v35
	s_waitcnt lgkmcnt(2)
	v_mov_b32_e32 v54, v47
	s_waitcnt lgkmcnt(1)
	v_mov_b32_e32 v56, v49
	s_waitcnt lgkmcnt(0)
	v_mov_b32_e32 v58, v51
	s_waitcnt vmcnt(7)
	v_pk_fma_f32 v[2:3], v[156:157], v[34:35], v[2:3] op_sel_hi:[1,0,1]
	v_pk_fma_f32 v[0:1], v[154:155], v[34:35], v[0:1] op_sel_hi:[1,0,1]
	s_waitcnt vmcnt(6)
	v_pk_fma_f32 v[2:3], v[160:161], v[52:53], v[2:3] op_sel_hi:[1,0,1]
	v_pk_fma_f32 v[0:1], v[158:159], v[52:53], v[0:1] op_sel_hi:[1,0,1]
	s_waitcnt vmcnt(5)
	v_pk_fma_f32 v[2:3], v[164:165], v[46:47], v[2:3] op_sel_hi:[1,0,1]
	v_pk_fma_f32 v[0:1], v[162:163], v[46:47], v[0:1] op_sel_hi:[1,0,1]
	s_waitcnt vmcnt(4)
	v_pk_fma_f32 v[2:3], v[232:233], v[54:55], v[2:3] op_sel_hi:[1,0,1]
	v_pk_fma_f32 v[0:1], v[230:231], v[54:55], v[0:1] op_sel_hi:[1,0,1]
	s_waitcnt vmcnt(3)
	v_pk_fma_f32 v[2:3], v[236:237], v[48:49], v[2:3] op_sel_hi:[1,0,1]
	v_pk_fma_f32 v[0:1], v[234:235], v[48:49], v[0:1] op_sel_hi:[1,0,1]
	s_waitcnt vmcnt(2)
	v_pk_fma_f32 v[2:3], v[240:241], v[56:57], v[2:3] op_sel_hi:[1,0,1]
	v_pk_fma_f32 v[0:1], v[238:239], v[56:57], v[0:1] op_sel_hi:[1,0,1]
	s_waitcnt vmcnt(1)
	v_pk_fma_f32 v[2:3], v[244:245], v[50:51], v[2:3] op_sel_hi:[1,0,1]
	v_pk_fma_f32 v[0:1], v[242:243], v[50:51], v[0:1] op_sel_hi:[1,0,1]
	s_waitcnt vmcnt(0)
	v_pk_fma_f32 v[2:3], v[220:221], v[58:59], v[2:3] op_sel_hi:[1,0,1]
	v_pk_fma_f32 v[0:1], v[218:219], v[58:59], v[0:1] op_sel_hi:[1,0,1]
	ds_bpermute_b32 v4, v82, v0
	ds_bpermute_b32 v5, v82, v1
	ds_bpermute_b32 v6, v82, v2
	ds_bpermute_b32 v7, v82, v3
	s_and_saveexec_b64 s[6:7], s[0:1]
	s_cbranch_execz .LBB0_37
	s_mul_hi_i32 s5, s4, 0x16000
	s_mul_i32 s4, s4, 0x16000
	v_readlane_b32 s12, v251, 46
	s_add_u32 s4, s12, s4
	v_readlane_b32 s12, v251, 47
	s_addc_u32 s5, s12, s5
	s_lshl_b32 s12, s28, 2
	s_add_u32 s4, s4, s12
	s_waitcnt lgkmcnt(3)
	v_add_f32_e32 v4, v0, v4
	s_waitcnt lgkmcnt(2)
	v_add_f32_e32 v5, v1, v5
	s_addc_u32 s5, s5, 0
	v_lshlrev_b32_e32 v0, 2, v38
	v_mov_b32_e32 v1, v169
	s_waitcnt lgkmcnt(0)
	v_add_f32_e32 v7, v3, v7
	v_add_f32_e32 v6, v2, v6
	v_lshl_add_u64 v[2:3], s[4:5], 0, v[0:1]
	global_atomic_add_f32 v0, v4, s[4:5]
	v_add_co_u32_e32 v0, vcc, 0x5000, v2
	s_nop 1
	v_addc_co_u32_e32 v1, vcc, 0, v3, vcc
	global_atomic_add_f32 v[0:1], v5, off offset:2048
	v_add_co_u32_e32 v0, vcc, 0xb000, v2
	s_nop 1
	v_addc_co_u32_e32 v1, vcc, 0, v3, vcc
	global_atomic_add_f32 v[0:1], v6, off
	v_add_co_u32_e32 v0, vcc, 0x10000, v2
	s_nop 1
	v_addc_co_u32_e32 v1, vcc, 0, v3, vcc
	global_atomic_add_f32 v[0:1], v7, off offset:2048

; __device__ __forceinline__ void transpose_item(const float* W, int K, int N, bf16_t* WT, int k0, int src_n0, int dst_n0, LAS float* scr, int lane, const float* st, float* sw, const float* gt, size_t cstride) {
;     ...
;     if (st) { const int n = lane & 31, hf = lane >> 5; f32x4 a4 = {0.f, 0.f, 0.f, 0.f};
; #pragma unroll 8
;         for (int i = 0; i < 32; ++i) { const int kk = hf * 32 + i; a4 += *(const f32x4*)(st + (size_t)(k0 + kk) * NB) * scr[kk * 33 + n]; }
.LBB0_43:
	global_load_dwordx4 v[6:9], v[4:5], off offset:-64
	global_load_dwordx4 v[10:13], v[4:5], off offset:-48
	global_load_dwordx4 v[14:17], v[4:5], off offset:-32
	global_load_dwordx4 v[18:21], v[4:5], off offset:-16
	global_load_dwordx4 v[22:25], v[4:5], off
	global_load_dwordx4 v[26:29], v[4:5], off offset:16
	global_load_dwordx4 v[30:33], v[4:5], off offset:32
	global_load_dwordx4 v[42:45], v[4:5], off offset:48
	global_load_dwordx4 v[122:125], v[4:5], off offset:64
	global_load_dwordx4 v[126:129], v[4:5], off offset:80
	global_load_dwordx4 v[130:133], v[4:5], off offset:96
	global_load_dwordx4 v[134:137], v[4:5], off offset:112
	global_load_dwordx4 v[138:141], v[4:5], off offset:128
	global_load_dwordx4 v[142:145], v[4:5], off offset:144
	global_load_dwordx4 v[146:149], v[4:5], off offset:160
	global_load_dwordx4 v[150:153], v[4:5], off offset:176
	global_load_dwordx4 v[186:189], v[4:5], off offset:192
	global_load_dwordx4 v[190:193], v[4:5], off offset:208
	global_load_dwordx4 v[194:197], v[4:5], off offset:224
	global_load_dwordx4 v[198:201], v[4:5], off offset:240
	global_load_dwordx4 v[202:205], v[4:5], off offset:256
	global_load_dwordx4 v[206:209], v[4:5], off offset:272
	global_load_dwordx4 v[210:213], v[4:5], off offset:288
	global_load_dwordx4 v[214:217], v[4:5], off offset:304
	global_load_dwordx4 v[154:157], v[4:5], off offset:320
	global_load_dwordx4 v[158:161], v[4:5], off offset:336
	global_load_dwordx4 v[162:165], v[4:5], off offset:352
	global_load_dwordx4 v[230:233], v[4:5], off offset:368
	global_load_dwordx4 v[234:237], v[4:5], off offset:384
	global_load_dwordx4 v[238:241], v[4:5], off offset:400
	global_load_dwordx4 v[242:245], v[4:5], off offset:416
	global_load_dwordx4 v[218:221], v[4:5], off offset:432
	v_add_u32_e32 v41, s5, v83
	ds_read2_b32 v[34:35], v41 offset1:33
	ds_read2_b32 v[46:47], v41 offset0:66 offset1:99
	ds_read2_b32 v[48:49], v41 offset0:132 offset1:165
	ds_read2_b32 v[50:51], v41 offset0:198 offset1:231
	s_addk_i32 s5, 0x420
	s_waitcnt lgkmcnt(3)
	v_mov_b32_e32 v52, v35
	s_waitcnt lgkmcnt(2)
	v_mov_b32_e32 v54, v47
	s_waitcnt lgkmcnt(1)
	v_mov_b32_e32 v56, v49
	s_waitcnt lgkmcnt(0)
	v_mov_b32_e32 v58, v51
	s_waitcnt vmcnt(31)
	v_pk_fma_f32 v[2:3], v[8:9], v[34:35], v[2:3] op_sel_hi:[1,0,1]
	v_pk_fma_f32 v[0:1], v[6:7], v[34:35], v[0:1] op_sel_hi:[1,0,1]
	s_waitcnt vmcnt(30)
	v_pk_fma_f32 v[2:3], v[12:13], v[52:53], v[2:3] op_sel_hi:[1,0,1]
	v_pk_fma_f32 v[0:1], v[10:11], v[52:53], v[0:1] op_sel_hi:[1,0,1]
	s_waitcnt vmcnt(29)
	v_pk_fma_f32 v[2:3], v[16:17], v[46:47], v[2:3] op_sel_hi:[1,0,1]
	v_pk_fma_f32 v[0:1], v[14:15], v[46:47], v[0:1] op_sel_hi:[1,0,1]
	s_waitcnt vmcnt(28)
	v_pk_fma_f32 v[2:3], v[20:21], v[54:55], v[2:3] op_sel_hi:[1,0,1]
	v_pk_fma_f32 v[0:1], v[18:19], v[54:55], v[0:1] op_sel_hi:[1,0,1]
	s_waitcnt vmcnt(27)
	v_pk_fma_f32 v[2:3], v[24:25], v[48:49], v[2:3] op_sel_hi:[1,0,1]
	v_pk_fma_f32 v[0:1], v[22:23], v[48:49], v[0:1] op_sel_hi:[1,0,1]
	s_waitcnt vmcnt(26)
	v_pk_fma_f32 v[2:3], v[28:29], v[56:57], v[2:3] op_sel_hi:[1,0,1]
	v_pk_fma_f32 v[0:1], v[26:27], v[56:57], v[0:1] op_sel_hi:[1,0,1]
	s_waitcnt vmcnt(25)
	v_pk_fma_f32 v[2:3], v[32:33], v[50:51], v[2:3] op_sel_hi:[1,0,1]
	v_pk_fma_f32 v[0:1], v[30:31], v[50:51], v[0:1] op_sel_hi:[1,0,1]
	s_waitcnt vmcnt(24)
	v_pk_fma_f32 v[2:3], v[44:45], v[58:59], v[2:3] op_sel_hi:[1,0,1]
	v_pk_fma_f32 v[0:1], v[42:43], v[58:59], v[0:1] op_sel_hi:[1,0,1]
	v_add_u32_e32 v41, s5, v83
	ds_read2_b32 v[34:35], v41 offset1:33
	ds_read2_b32 v[46:47], v41 offset0:66 offset1:99
	ds_read2_b32 v[48:49], v41 offset0:132 offset1:165
	ds_read2_b32 v[50:51], v41 offset0:198 offset1:231
	s_addk_i32 s5, 0x420
	s_waitcnt lgkmcnt(3)
	v_mov_b32_e32 v52, v35
	s_waitcnt lgkmcnt(2)
	v_mov_b32_e32 v54, v47
	s_waitcnt lgkmcnt(1)
	v_mov_b32_e32 v56, v49
	s_waitcnt lgkmcnt(0)
	v_mov_b32_e32 v58, v51
	s_waitcnt vmcnt(23)
	v_pk_fma_f32 v[2:3], v[124:125], v[34:35], v[2:3] op_sel_hi:[1,0,1]
	v_pk_fma_f32 v[0:1], v[122:123], v[34:35], v[0:1] op_sel_hi:[1,0,1]
	s_waitcnt vmcnt(22)
	v_pk_fma_f32 v[2:3], v[128:129], v[52:53], v[2:3] op_sel_hi:[1,0,1]
	v_pk_fma_f32 v[0:1], v[126:127], v[52:53], v[0:1] op_sel_hi:[1,0,1]
	s_waitcnt vmcnt(21)
	v_pk_fma_f32 v[2:3], v[132:133], v[46:47], v[2:3] op_sel_hi:[1,0,1]
	v_pk_fma_f32 v[0:1], v[130:131], v[46:47], v[0:1] op_sel_hi:[1,0,1]
	s_waitcnt vmcnt(20)
	v_pk_fma_f32 v[2:3], v[136:137], v[54:55], v[2:3] op_sel_hi:[1,0,1]
	v_pk_fma_f32 v[0:1], v[134:135], v[54:55], v[0:1] op_sel_hi:[1,0,1]
	s_waitcnt vmcnt(19)
	v_pk_fma_f32 v[2:3], v[140:141], v[48:49], v[2:3] op_sel_hi:[1,0,1]
	v_pk_fma_f32 v[0:1], v[138:139], v[48:49], v[0:1] op_sel_hi:[1,0,1]
	s_waitcnt vmcnt(18)
	v_pk_fma_f32 v[2:3], v[144:145], v[56:57], v[2:3] op_sel_hi:[1,0,1]
	v_pk_fma_f32 v[0:1], v[142:143], v[56:57], v[0:1] op_sel_hi:[1,0,1]
	s_waitcnt vmcnt(17)
; __device__ __forceinline__ void transpose_item(const float* W, int K, int N, bf16_t* WT, int k0, int src_n0, int dst_n0, LAS float* scr, int lane, const float* st, float* sw, const float* gt, size_t cstride) {
;     ...
;     if (st) { const int n = lane & 31, hf = lane >> 5; f32x4 a4 = {0.f, 0.f, 0.f, 0.f};
; #pragma unroll 8
;         for (int i = 0; i < 32; ++i) { const int kk = hf * 32 + i; a4 += *(const f32x4*)(st + (size_t)(k0 + kk) * NB) * scr[kk * 33 + n]; }
; #pragma unroll
;         for (int b = 0; b < 4; ++b) a4[b] += __shfl_xor(a4[b], 32);
;         if (hf == 0) {
; #pragma unroll
;             for (int b = 0; b < 4; ++b) __hip_atomic_fetch_add(sw + (size_t)b * NSW + dst_n0 + n, a4[b], __ATOMIC_RELAXED, __HIP_MEMORY_SCOPE_AGENT); } }
	v_pk_fma_f32 v[2:3], v[148:149], v[50:51], v[2:3] op_sel_hi:[1,0,1]
	v_pk_fma_f32 v[0:1], v[146:147], v[50:51], v[0:1] op_sel_hi:[1,0,1]
	s_waitcnt vmcnt(16)
	v_pk_fma_f32 v[2:3], v[152:153], v[58:59], v[2:3] op_sel_hi:[1,0,1]
	v_pk_fma_f32 v[0:1], v[150:151], v[58:59], v[0:1] op_sel_hi:[1,0,1]
	v_add_u32_e32 v41, s5, v83
	ds_read2_b32 v[34:35], v41 offset1:33
	ds_read2_b32 v[46:47], v41 offset0:66 offset1:99
	ds_read2_b32 v[48:49], v41 offset0:132 offset1:165
	ds_read2_b32 v[50:51], v41 offset0:198 offset1:231
	s_addk_i32 s5, 0x420
	s_waitcnt lgkmcnt(3)
	v_mov_b32_e32 v52, v35
	s_waitcnt lgkmcnt(2)
	v_mov_b32_e32 v54, v47
	s_waitcnt lgkmcnt(1)
	v_mov_b32_e32 v56, v49
	s_waitcnt lgkmcnt(0)
	v_mov_b32_e32 v58, v51
	s_waitcnt vmcnt(15)
	v_pk_fma_f32 v[2:3], v[188:189], v[34:35], v[2:3] op_sel_hi:[1,0,1]
	v_pk_fma_f32 v[0:1], v[186:187], v[34:35], v[0:1] op_sel_hi:[1,0,1]
	s_waitcnt vmcnt(14)
	v_pk_fma_f32 v[2:3], v[192:193], v[52:53], v[2:3] op_sel_hi:[1,0,1]
	v_pk_fma_f32 v[0:1], v[190:191], v[52:53], v[0:1] op_sel_hi:[1,0,1]
	s_waitcnt vmcnt(13)
	v_pk_fma_f32 v[2:3], v[196:197], v[46:47], v[2:3] op_sel_hi:[1,0,1]
	v_pk_fma_f32 v[0:1], v[194:195], v[46:47], v[0:1] op_sel_hi:[1,0,1]
	s_waitcnt vmcnt(12)
	v_pk_fma_f32 v[2:3], v[200:201], v[54:55], v[2:3] op_sel_hi:[1,0,1]
	v_pk_fma_f32 v[0:1], v[198:199], v[54:55], v[0:1] op_sel_hi:[1,0,1]
	s_waitcnt vmcnt(11)
	v_pk_fma_f32 v[2:3], v[204:205], v[48:49], v[2:3] op_sel_hi:[1,0,1]
	v_pk_fma_f32 v[0:1], v[202:203], v[48:49], v[0:1] op_sel_hi:[1,0,1]
	s_waitcnt vmcnt(10)
	v_pk_fma_f32 v[2:3], v[208:209], v[56:57], v[2:3] op_sel_hi:[1,0,1]
	v_pk_fma_f32 v[0:1], v[206:207], v[56:57], v[0:1] op_sel_hi:[1,0,1]
	s_waitcnt vmcnt(9)
	v_pk_fma_f32 v[2:3], v[212:213], v[50:51], v[2:3] op_sel_hi:[1,0,1]
	v_pk_fma_f32 v[0:1], v[210:211], v[50:51], v[0:1] op_sel_hi:[1,0,1]
	s_waitcnt vmcnt(8)
	v_pk_fma_f32 v[2:3], v[216:217], v[58:59], v[2:3] op_sel_hi:[1,0,1]
	v_pk_fma_f32 v[0:1], v[214:215], v[58:59], v[0:1] op_sel_hi:[1,0,1]
	v_add_u32_e32 v41, s5, v83
	ds_read2_b32 v[34:35], v41 offset1:33
	ds_read2_b32 v[46:47], v41 offset0:66 offset1:99
	ds_read2_b32 v[48:49], v41 offset0:132 offset1:165
	ds_read2_b32 v[50:51], v41 offset0:198 offset1:231
	s_addk_i32 s5, 0x420
	s_waitcnt lgkmcnt(3)
	v_mov_b32_e32 v52, v35
	s_waitcnt lgkmcnt(2)
	v_mov_b32_e32 v54, v47
	s_waitcnt lgkmcnt(1)
	v_mov_b32_e32 v56, v49
	s_waitcnt lgkmcnt(0)
	v_mov_b32_e32 v58, v51
	s_waitcnt vmcnt(7)
	v_pk_fma_f32 v[2:3], v[156:157], v[34:35], v[2:3] op_sel_hi:[1,0,1]
	v_pk_fma_f32 v[0:1], v[154:155], v[34:35], v[0:1] op_sel_hi:[1,0,1]
	s_waitcnt vmcnt(6)
	v_pk_fma_f32 v[2:3], v[160:161], v[52:53], v[2:3] op_sel_hi:[1,0,1]
	v_pk_fma_f32 v[0:1], v[158:159], v[52:53], v[0:1] op_sel_hi:[1,0,1]
	s_waitcnt vmcnt(5)
	v_pk_fma_f32 v[2:3], v[164:165], v[46:47], v[2:3] op_sel_hi:[1,0,1]
	v_pk_fma_f32 v[0:1], v[162:163], v[46:47], v[0:1] op_sel_hi:[1,0,1]
	s_waitcnt vmcnt(4)
	v_pk_fma_f32 v[2:3], v[232:233], v[54:55], v[2:3] op_sel_hi:[1,0,1]
	v_pk_fma_f32 v[0:1], v[230:231], v[54:55], v[0:1] op_sel_hi:[1,0,1]
	s_waitcnt vmcnt(3)
	v_pk_fma_f32 v[2:3], v[236:237], v[48:49], v[2:3] op_sel_hi:[1,0,1]
	v_pk_fma_f32 v[0:1], v[234:235], v[48:49], v[0:1] op_sel_hi:[1,0,1]
	s_waitcnt vmcnt(2)
	v_pk_fma_f32 v[2:3], v[240:241], v[56:57], v[2:3] op_sel_hi:[1,0,1]
	v_pk_fma_f32 v[0:1], v[238:239], v[56:57], v[0:1] op_sel_hi:[1,0,1]
	s_waitcnt vmcnt(1)
	v_pk_fma_f32 v[2:3], v[244:245], v[50:51], v[2:3] op_sel_hi:[1,0,1]
	v_pk_fma_f32 v[0:1], v[242:243], v[50:51], v[0:1] op_sel_hi:[1,0,1]
	s_waitcnt vmcnt(0)
	v_pk_fma_f32 v[2:3], v[220:221], v[58:59], v[2:3] op_sel_hi:[1,0,1]
	v_pk_fma_f32 v[0:1], v[218:219], v[58:59], v[0:1] op_sel_hi:[1,0,1]
	ds_bpermute_b32 v4, v82, v0
	ds_bpermute_b32 v5, v82, v1
	ds_bpermute_b32 v6, v82, v2
	ds_bpermute_b32 v7, v82, v3
	s_and_saveexec_b64 s[24:25], s[0:1]
	s_cbranch_execz .LBB0_24
	s_mul_hi_i32 s5, s6, 0x16000
	s_mul_i32 s6, s6, 0x16000
	v_readlane_b32 s7, v251, 46
	s_add_u32 s6, s7, s6
	v_readlane_b32 s7, v251, 47
	s_addc_u32 s7, s7, s5
	s_ashr_i32 s5, s4, 31
	s_lshl_b64 s[4:5], s[4:5], 2
	s_add_u32 s4, s6, s4
	s_waitcnt lgkmcnt(3)
	v_add_f32_e32 v4, v0, v4
	s_waitcnt lgkmcnt(2)
	v_add_f32_e32 v5, v1, v5
	s_addc_u32 s5, s7, s5
	v_lshlrev_b32_e32 v0, 2, v38
	v_mov_b32_e32 v1, v169
	s_waitcnt lgkmcnt(0)
	v_add_f32_e32 v7, v3, v7
	v_add_f32_e32 v6, v2, v6
	v_lshl_add_u64 v[2:3], s[4:5], 0, v[0:1]
	global_atomic_add_f32 v0, v4, s[4:5]
	v_add_co_u32_e32 v0, vcc, 0x5000, v2
	s_nop 1
	v_addc_co_u32_e32 v1, vcc, 0, v3, vcc
	global_atomic_add_f32 v[0:1], v5, off offset:2048
	v_add_co_u32_e32 v0, vcc, 0xb000, v2
	s_nop 1
	v_addc_co_u32_e32 v1, vcc, 0, v3, vcc
	global_atomic_add_f32 v[0:1], v6, off
	v_add_co_u32_e32 v0, vcc, 0x10000, v2
	s_nop 1
	v_addc_co_u32_e32 v1, vcc, 0, v3, vcc
	global_atomic_add_f32 v[0:1], v7, off offset:2048
	s_branch .LBB0_24

; __device__ __forceinline__ void mod_phase(const In& I, unsigned char* ws, LAS unsigned char* lds, int tid, int lane, int wave) {
;     ...
;     for (int i = tid; i < NB * DM; i += NTHR) { const float v = I.c[i]; sc[i] = v / (1.0f + __expf(-v)); }
.LBB0_436:
	global_load_dword v11, v[0:1], off
	global_load_dword v12, v[0:1], off offset:2048
	s_mov_b64 s[4:5], 0x1000
	v_lshl_add_u64 v[20:21], v[0:1], 0, s[4:5]
	global_load_dword v13, v[20:21], off
	global_load_dword v14, v[20:21], off offset:2048
	v_lshl_add_u64 v[20:21], v[20:21], 0, s[4:5]
	global_load_dword v15, v[20:21], off
	global_load_dword v16, v[20:21], off offset:2048
	v_lshl_add_u64 v[20:21], v[20:21], 0, s[4:5]
	global_load_dword v17, v[20:21], off
	global_load_dword v18, v[20:21], off offset:2048
	s_waitcnt vmcnt(7)
	v_mov_b32_e32 v4, v11
	v_mul_f32_e32 v5, 0xbfb8aa3b, v4
	v_exp_f32_e32 v5, v5
	s_nop 0
	v_add_f32_e32 v5, 1.0, v5
	v_div_scale_f32 v6, s[4:5], v5, v5, v4
	v_rcp_f32_e32 v7, v6
	v_div_scale_f32 v8, vcc, v4, v5, v4
	v_fma_f32 v9, -v6, v7, 1.0
	v_fmac_f32_e32 v7, v9, v7
	v_mul_f32_e32 v9, v8, v7
	v_fma_f32 v10, -v6, v9, v8
	v_fmac_f32_e32 v9, v10, v7
	v_fma_f32 v6, -v6, v9, v8
	v_div_fmas_f32 v6, v6, v7, v9
	v_div_fixup_f32 v4, v6, v5, v4
	ds_write_b32 v3, v4
	s_waitcnt vmcnt(6)
	v_mov_b32_e32 v4, v12
	v_mul_f32_e32 v5, 0xbfb8aa3b, v4
	v_exp_f32_e32 v5, v5
	s_nop 0
	v_add_f32_e32 v5, 1.0, v5
	v_div_scale_f32 v6, s[4:5], v5, v5, v4
	v_rcp_f32_e32 v7, v6
	v_div_scale_f32 v8, vcc, v4, v5, v4
	v_fma_f32 v9, -v6, v7, 1.0
	v_fmac_f32_e32 v7, v9, v7
	v_mul_f32_e32 v9, v8, v7
	v_fma_f32 v10, -v6, v9, v8
	v_fmac_f32_e32 v9, v10, v7
	v_fma_f32 v6, -v6, v9, v8
	v_div_fmas_f32 v6, v6, v7, v9
	v_div_fixup_f32 v4, v6, v5, v4
	ds_write_b32 v3, v4 offset:2048
	s_waitcnt vmcnt(5)
	v_mov_b32_e32 v4, v13
	v_mul_f32_e32 v5, 0xbfb8aa3b, v4
	v_exp_f32_e32 v5, v5
	s_nop 0
	v_add_f32_e32 v5, 1.0, v5
	v_div_scale_f32 v6, s[4:5], v5, v5, v4
	v_rcp_f32_e32 v7, v6
	v_div_scale_f32 v8, vcc, v4, v5, v4
	v_fma_f32 v9, -v6, v7, 1.0
	v_fmac_f32_e32 v7, v9, v7
	v_mul_f32_e32 v9, v8, v7
	v_fma_f32 v10, -v6, v9, v8
	v_fmac_f32_e32 v9, v10, v7
	v_fma_f32 v6, -v6, v9, v8
	v_div_fmas_f32 v6, v6, v7, v9
	v_div_fixup_f32 v4, v6, v5, v4
	ds_write_b32 v3, v4 offset:4096
	s_waitcnt vmcnt(4)
	v_mov_b32_e32 v4, v14
	v_mul_f32_e32 v5, 0xbfb8aa3b, v4
	v_exp_f32_e32 v5, v5
	s_nop 0
	v_add_f32_e32 v5, 1.0, v5
	v_div_scale_f32 v6, s[4:5], v5, v5, v4
	v_rcp_f32_e32 v7, v6
	v_div_scale_f32 v8, vcc, v4, v5, v4
	v_fma_f32 v9, -v6, v7, 1.0
	v_fmac_f32_e32 v7, v9, v7
	v_mul_f32_e32 v9, v8, v7
	v_fma_f32 v10, -v6, v9, v8
	v_fmac_f32_e32 v9, v10, v7
	v_fma_f32 v6, -v6, v9, v8
	v_div_fmas_f32 v6, v6, v7, v9
	v_div_fixup_f32 v4, v6, v5, v4
	ds_write_b32 v3, v4 offset:6144
	s_waitcnt vmcnt(3)
	v_mov_b32_e32 v4, v15
	v_mul_f32_e32 v5, 0xbfb8aa3b, v4
	v_exp_f32_e32 v5, v5
	s_nop 0
	v_add_f32_e32 v5, 1.0, v5
	v_div_scale_f32 v6, s[4:5], v5, v5, v4
	v_rcp_f32_e32 v7, v6
	v_div_scale_f32 v8, vcc, v4, v5, v4
	v_fma_f32 v9, -v6, v7, 1.0
	v_fmac_f32_e32 v7, v9, v7
	v_mul_f32_e32 v9, v8, v7
	v_fma_f32 v10, -v6, v9, v8
	v_fmac_f32_e32 v9, v10, v7
	v_fma_f32 v6, -v6, v9, v8
	v_div_fmas_f32 v6, v6, v7, v9
	v_div_fixup_f32 v4, v6, v5, v4
	ds_write_b32 v3, v4 offset:8192
	s_waitcnt vmcnt(2)
	v_mov_b32_e32 v4, v16
	v_mul_f32_e32 v5, 0xbfb8aa3b, v4
	v_exp_f32_e32 v5, v5
	s_nop 0
	v_add_f32_e32 v5, 1.0, v5
	v_div_scale_f32 v6, s[4:5], v5, v5, v4
	v_rcp_f32_e32 v7, v6
	v_div_scale_f32 v8, vcc, v4, v5, v4
	v_fma_f32 v9, -v6, v7, 1.0
	v_fmac_f32_e32 v7, v9, v7
	v_mul_f32_e32 v9, v8, v7
	v_fma_f32 v10, -v6, v9, v8
	v_fmac_f32_e32 v9, v10, v7
	v_fma_f32 v6, -v6, v9, v8
	v_div_fmas_f32 v6, v6, v7, v9
	v_div_fixup_f32 v4, v6, v5, v4
	ds_write_b32 v3, v4 offset:10240
	s_waitcnt vmcnt(1)
	v_mov_b32_e32 v4, v17
	v_mul_f32_e32 v5, 0xbfb8aa3b, v4
	v_exp_f32_e32 v5, v5
	s_nop 0
	v_add_f32_e32 v5, 1.0, v5
	v_div_scale_f32 v6, s[4:5], v5, v5, v4
	v_rcp_f32_e32 v7, v6
	v_div_scale_f32 v8, vcc, v4, v5, v4
	v_fma_f32 v9, -v6, v7, 1.0
	v_fmac_f32_e32 v7, v9, v7
	v_mul_f32_e32 v9, v8, v7
	v_fma_f32 v10, -v6, v9, v8
	v_fmac_f32_e32 v9, v10, v7
	v_fma_f32 v6, -v6, v9, v8
	v_div_fmas_f32 v6, v6, v7, v9
	v_div_fixup_f32 v4, v6, v5, v4
	ds_write_b32 v3, v4 offset:12288
	s_waitcnt vmcnt(0)
	v_mov_b32_e32 v4, v18
	v_mul_f32_e32 v5, 0xbfb8aa3b, v4
	v_exp_f32_e32 v5, v5
	s_nop 0
	v_add_f32_e32 v5, 1.0, v5
	v_div_scale_f32 v6, s[4:5], v5, v5, v4
	v_rcp_f32_e32 v7, v6
	v_div_scale_f32 v8, vcc, v4, v5, v4
	v_fma_f32 v9, -v6, v7, 1.0
	v_fmac_f32_e32 v7, v9, v7
	v_mul_f32_e32 v9, v8, v7
	v_fma_f32 v10, -v6, v9, v8
	v_fmac_f32_e32 v9, v10, v7
	v_fma_f32 v6, -v6, v9, v8
	v_div_fmas_f32 v6, v6, v7, v9
	v_div_fixup_f32 v4, v6, v5, v4
	ds_write_b32 v3, v4 offset:14336
